# code placement: 8 bytes of padding (unreachable) behind the attention loop shift the later phases' hot loops
# speedup vs baseline: 1.0032x; 1.0032x over previous
; __global__ void __launch_bounds__(512, 2) fwd_kernel(Args a) {
;     ...
;         for (int i = 0;; ++i) {
;             const int v = (i & 1) ? (G - 1 - (int)blockIdx.x) : (int)blockIdx.x;
;             const int p = i * G + v;
;             if (i * G >= NU) break;
;             if (p >= NU) continue;
;             int bh, qpos0, ntiles, slim;
;             if (p < 2048) { const int jq = 127 - (p >> 4); bh = p & 15; qpos0 = NMETA + 128 * jq; ntiles = 2 * jq + 3; slim = LSEQ; }
;             else { bh = p - 2048; qpos0 = 0; ntiles = 1; slim = NMETA; }
;             att::attn_unit(lds, BIG, KIMG, VIMG, Z, bh >> 3, bh & 7, qpos0, ntiles, slim, a.relb, a.subg, lam, 1.0f - lam_init);
;         }
.LBB0_753:
	s_add_i32 s41, s41, 1
	s_mov_b64 s[0:1], 0
	s_branch .LBB0_666
	s_nop 0
	s_nop 0
